# first K-iteration of each GEMM tile peeled with srcC=0 MFMAs, accumulator zeroing v_mov removed (GEMM1, GEMM3, GEMM4)
# speedup vs baseline: 1.0152x; 1.0015x over previous
;     __host__ __device__ bool next(int i, Unit& u) const { const int L = i * G + c; if (L >= 4 * nM) return false; u.pm = L >> 2; u.pn = 0; u.kq = L & 3; return true; }
; #define PG8_STAGE(bufoff, gbase, voff) do { _Pragma("unroll") for (int _i = 0; _i < 2; ++_i) \
;         __builtin_amdgcn_global_load_lds((const unsigned*)((const char*)(gbase) + (voff)[_i]), (PG8_LAS unsigned*)(lds + (bufoff) + ldsw + _i * 8192), 16, 0, 0); } while (0)
; #define PG8_LDA(dst, b, h) do { _Pragma("unroll") for (int m = 0; m < 4; ++m) _Pragma("unroll") for (int k = 0; k < 2; ++k) dst[m][k] = *(const PG8_LAS bf16x8*)(lds + PG8_SA(b, h) + aoff + m * 2048 + k * 1024); } while (0)
; #define PG8_LDB(dst, b, h) do { _Pragma("unroll") for (int n = 0; n < 2; ++n) _Pragma("unroll") for (int k = 0; k < 2; ++k) dst[n][k] = *(const PG8_LAS bf16x8*)(lds + PG8_SB(b, h) + boff + n * 2048 + k * 1024); } while (0)
; template <class Epi, class Sched, bool ALIGN_EPI = false, bool SP2 = false>
; __device__ __forceinline__ void gemm_phase(PG8_LAS unsigned char* lds, const Gemm g, const Sched& S, const Epi& E) {
;     ...
;     for (;;) {
;         const bool has_next = S.next(ui + 1, nxt);
;         const char* nA = has_next ? (const char*)g.A + (size_t)nxt.pm * tstepA + nxt.kq * g.kq_bytes : cA; const char* nB = has_next ? (const char*)g.Bt + (size_t)nxt.pn * tstepB + nxt.kq * g.kq_bytes : cB;
;         for (int t = 0; t < nt; t += 2) {
;             const bool last = (t == nt - 2);
;             const char* a1 = cA + (size_t)(t + 1) * kstep + (t >= g.kj_t ? g.kj_bytes : 0);
;             const char* a2 = last ? nA : cA + (size_t)(t + 2) * kstep + (t + 2 >= g.kj_t ? g.kj_bytes : 0); const char* b2 = last ? nB : cB + (size_t)(t + 2) * kstep;
;             const char* a3 = a2 + kstep; const char* b3 = b2 + kstep;
;             if (last && has_next) S.a_ready(nxt);
;             if constexpr (Epi::MIDK) { if (t == g.kj_t) E.midk(acc, cur, wr, fr); }
;             if constexpr (SP2) {
;             PG8_LDB(B0, 0, 0); PG8_LDB(B1, 0, 1); PG8_SCHED; PG8_LDA(At, 0, 0); PG8_STAGE(PG8_SA(1, 1), a1 + hstepA, voffA);
;             PG8_WAIT_V(8); PG8_WAIT_L(0); PG8_BAR; PG8_MMA(0, 0, At, B0); PG8_MMA(0, 1, At, B1); PG8_BAR; PG8_SCHED;
;             PG8_LDA(At, 0, 1); PG8_STAGE(PG8_SB(0, 0), b2, voffB); PG8_STAGE(PG8_SB(0, 1), b2 + hstepB, voffB); PG8_STAGE(PG8_SA(0, 0), a2, voffA);
.LBB0_78:
	s_ashr_i32 s17, s16, 31
	s_lshl_b64 s[18:19], s[16:17], 21
	s_add_u32 s18, s42, s18
	s_addc_u32 s19, s43, s19
	s_and_b64 s[20:21], s[4:5], exec
	s_cselect_b32 s17, s19, s23
	s_cselect_b32 s60, s18, s22
	s_ashr_i32 s15, s14, 31
	s_lshl_b64 s[20:21], s[14:15], 21
	s_add_u32 s20, s70, s20
	s_addc_u32 s21, s71, s21
	s_and_b64 s[26:27], s[4:5], exec
	s_cselect_b32 s15, s21, s25
	s_cselect_b32 s61, s20, s24
	s_add_u32 s22, s22, 0x100080
	s_addc_u32 s23, s23, 0
	s_add_u32 s62, s24, 0x100
	s_addc_u32 s63, s25, 0
	s_mov_b32 s64, -2
	ds_read_b128 v[152:155], v148
	ds_read_b128 v[156:159], v148 offset:1024
	ds_read_b128 v[160:163], v148 offset:2048
	ds_read_b128 v[168:171], v148 offset:3072
	ds_read_b128 v[172:175], v149
	ds_read_b128 v[176:179], v149 offset:1024
	ds_read_b128 v[180:183], v149 offset:2048
	ds_read_b128 v[184:187], v149 offset:3072
	s_add_u32 s24, s22, 0xfff00080
	s_addc_u32 s25, s23, -1
	s_cmp_eq_u32 s64, 60
	s_cselect_b32 s27, s17, s25
	s_cselect_b32 s26, s60, s24
	s_cselect_b32 s25, s15, s63
	s_cselect_b32 s24, s61, s62
	s_add_u32 s98, s24, 0x80
	s_addc_u32 s99, s25, 0
	s_add_u32 s100, s26, 0x80
	s_addc_u32 s101, s27, 0
	s_add_i32 m0, s13, 0xc000
	ds_read_b128 v[188:191], v150
	ds_read_b128 v[192:195], v150 offset:1024
	ds_read_b128 v[196:199], v150 offset:2048
	ds_read_b128 v[200:203], v150 offset:3072
	ds_read_b128 v[204:207], v150 offset:4096
	ds_read_b128 v[208:211], v150 offset:5120
	ds_read_b128 v[212:215], v150 offset:6144
	ds_read_b128 v[216:219], v150 offset:7168
	global_load_lds_dwordx4 v138, s[22:23]
	s_add_i32 m0, s13, 0xe000
	s_nop 0
	global_load_lds_dwordx4 v140, s[22:23]
	s_waitcnt vmcnt(8)
	s_waitcnt lgkmcnt(0)
	s_barrier
	s_setprio 1
	s_waitcnt lgkmcnt(0)
	v_mfma_f32_16x16x32_bf16 v[126:129], v[152:155], v[188:191], 0
	v_mfma_f32_16x16x32_bf16 v[126:129], v[156:159], v[192:195], v[126:129]
	v_mfma_f32_16x16x32_bf16 v[122:125], v[168:171], v[192:195], 0
	v_mfma_f32_16x16x32_bf16 v[122:125], v[160:163], v[188:191], v[122:125]
	v_mfma_f32_16x16x32_bf16 v[114:117], v[160:163], v[196:199], 0
	v_mfma_f32_16x16x32_bf16 v[114:117], v[168:171], v[200:203], v[114:117]
	v_mfma_f32_16x16x32_bf16 v[118:121], v[156:159], v[200:203], 0
	v_mfma_f32_16x16x32_bf16 v[118:121], v[152:155], v[196:199], v[118:121]
	v_mfma_f32_16x16x32_bf16 v[102:105], v[152:155], v[204:207], 0
	v_mfma_f32_16x16x32_bf16 v[102:105], v[156:159], v[208:211], v[102:105]
	v_mfma_f32_16x16x32_bf16 v[98:101], v[168:171], v[208:211], 0
	v_mfma_f32_16x16x32_bf16 v[98:101], v[160:163], v[204:207], v[98:101]
	v_mfma_f32_16x16x32_bf16 v[82:85], v[160:163], v[212:215], 0
	v_mfma_f32_16x16x32_bf16 v[82:85], v[168:171], v[216:219], v[82:85]
	v_mfma_f32_16x16x32_bf16 v[86:89], v[156:159], v[216:219], 0
	v_mfma_f32_16x16x32_bf16 v[86:89], v[152:155], v[212:215], v[86:89]
	v_mfma_f32_16x16x32_bf16 v[110:113], v[172:175], v[188:191], 0
	v_mfma_f32_16x16x32_bf16 v[110:113], v[176:179], v[192:195], v[110:113]
	v_mfma_f32_16x16x32_bf16 v[106:109], v[184:187], v[192:195], 0
	v_mfma_f32_16x16x32_bf16 v[106:109], v[180:183], v[188:191], v[106:109]
	v_mfma_f32_16x16x32_bf16 v[90:93], v[180:183], v[196:199], 0
	v_mfma_f32_16x16x32_bf16 v[90:93], v[184:187], v[200:203], v[90:93]
	v_mfma_f32_16x16x32_bf16 v[94:97], v[176:179], v[200:203], 0
	v_mfma_f32_16x16x32_bf16 v[94:97], v[172:175], v[196:199], v[94:97]
	v_mfma_f32_16x16x32_bf16 v[78:81], v[172:175], v[204:207], 0
	v_mfma_f32_16x16x32_bf16 v[78:81], v[176:179], v[208:211], v[78:81]
	v_mfma_f32_16x16x32_bf16 v[74:77], v[184:187], v[208:211], 0
	v_mfma_f32_16x16x32_bf16 v[74:77], v[180:183], v[204:207], v[74:77]
	v_mfma_f32_16x16x32_bf16 v[66:69], v[180:183], v[212:215], 0
	v_mfma_f32_16x16x32_bf16 v[66:69], v[184:187], v[216:219], v[66:69]
	s_setprio 2
	s_barrier
	v_mfma_f32_16x16x32_bf16 v[70:73], v[176:179], v[216:219], 0
	v_mfma_f32_16x16x32_bf16 v[70:73], v[172:175], v[212:215], v[70:73]
	s_setprio 0
	s_add_i32 s65, s38, s3
	s_mov_b32 m0, s65
	ds_read_b128 v[188:191], v150 offset:16384
	ds_read_b128 v[192:195], v150 offset:17408
	ds_read_b128 v[196:199], v150 offset:18432
	ds_read_b128 v[200:203], v150 offset:19456
	ds_read_b128 v[204:207], v150 offset:20480
	ds_read_b128 v[208:211], v150 offset:21504
	ds_read_b128 v[212:215], v150 offset:22528
	ds_read_b128 v[216:219], v150 offset:23552
	global_load_lds_dwordx4 v134, s[24:25]
	s_add_i32 m0, s65, 0x2000
	s_add_u32 s66, s24, 0x100000
	s_addc_u32 s67, s25, 0
	s_add_i32 s65, s39, s3
	global_load_lds_dwordx4 v130, s[24:25]
	s_mov_b32 m0, s65
	s_nop 0
	global_load_lds_dwordx4 v134, s[66:67]
	s_add_i32 m0, s65, 0x2000
	s_nop 0
	global_load_lds_dwordx4 v130, s[66:67]
	s_mov_b32 m0, s13
	s_nop 0
	global_load_lds_dwordx4 v136, s[26:27]
	s_mov_b32 m0, s30
	s_nop 0
	global_load_lds_dwordx4 v132, s[26:27]
	s_waitcnt vmcnt(8)
	s_waitcnt lgkmcnt(0)
	s_barrier
; #define PG8_STAGE(bufoff, gbase, voff) do { _Pragma("unroll") for (int _i = 0; _i < 2; ++_i) \
;         __builtin_amdgcn_global_load_lds((const unsigned*)((const char*)(gbase) + (voff)[_i]), (PG8_LAS unsigned*)(lds + (bufoff) + ldsw + _i * 8192), 16, 0, 0); } while (0)
; #define PG8_LDA(dst, b, h) do { _Pragma("unroll") for (int m = 0; m < 4; ++m) _Pragma("unroll") for (int k = 0; k < 2; ++k) dst[m][k] = *(const PG8_LAS bf16x8*)(lds + PG8_SA(b, h) + aoff + m * 2048 + k * 1024); } while (0)
; #define PG8_LDB(dst, b, h) do { _Pragma("unroll") for (int n = 0; n < 2; ++n) _Pragma("unroll") for (int k = 0; k < 2; ++k) dst[n][k] = *(const PG8_LAS bf16x8*)(lds + PG8_SB(b, h) + boff + n * 2048 + k * 1024); } while (0)
; #define PG8_MMA(ai, bj, At, Bt) do { __builtin_amdgcn_s_setprio(1); _Pragma("unroll") for (int m = 0; m < 4; ++m) _Pragma("unroll") for (int n = 0; n < 2; ++n) _Pragma("unroll") for (int k = 0; k < 2; ++k) \
;         acc[ai][bj][m][n] = __builtin_amdgcn_mfma_f32_16x16x32_bf16(Bt[n][k], At[m][k], acc[ai][bj][m][n], 0, 0, 0); __builtin_amdgcn_s_setprio(0); } while (0)
; #define PG8_WAIT_V(n) asm volatile("s_waitcnt vmcnt(" #n ")" ::: "memory")
; #define PG8_WAIT_L(n) asm volatile("s_waitcnt lgkmcnt(" #n ")" ::: "memory")
; #define PG8_BAR __builtin_amdgcn_s_barrier()
; #define PG8_SCHED __builtin_amdgcn_sched_barrier(0)
; template <class Epi, class Sched, bool ALIGN_EPI = false, bool SP2 = false>
; __device__ __forceinline__ void gemm_phase(PG8_LAS unsigned char* lds, const Gemm g, const Sched& S, const Epi& E) {
;     ...
;             PG8_WAIT_V(8); PG8_WAIT_L(0); PG8_BAR; PG8_MMA(1, 0, At, B0); PG8_MMA(1, 1, At, B1); PG8_BAR; PG8_SCHED;
;             PG8_LDB(B0, 1, 0); PG8_LDB(B1, 1, 1); PG8_SCHED; PG8_LDA(At, 1, 0); PG8_STAGE(PG8_SA(0, 1), a2 + hstepA, voffA);
;             PG8_WAIT_V(8); PG8_WAIT_L(0); PG8_BAR; PG8_MMA(0, 0, At, B0); PG8_MMA(0, 1, At, B1); PG8_BAR; PG8_SCHED;
;             PG8_LDA(At, 1, 1); PG8_STAGE(PG8_SB(1, 0), b3, voffB); PG8_STAGE(PG8_SB(1, 1), b3 + hstepB, voffB); PG8_STAGE(PG8_SA(1, 0), a3, voffA);
	s_setprio 1
	s_waitcnt lgkmcnt(0)
	v_mfma_f32_16x16x32_bf16 v[62:65], v[152:155], v[188:191], 0
	v_mfma_f32_16x16x32_bf16 v[62:65], v[156:159], v[192:195], v[62:65]
	v_mfma_f32_16x16x32_bf16 v[58:61], v[168:171], v[192:195], 0
	v_mfma_f32_16x16x32_bf16 v[58:61], v[160:163], v[188:191], v[58:61]
	v_mfma_f32_16x16x32_bf16 v[50:53], v[160:163], v[196:199], 0
	v_mfma_f32_16x16x32_bf16 v[50:53], v[168:171], v[200:203], v[50:53]
	v_mfma_f32_16x16x32_bf16 v[54:57], v[156:159], v[200:203], 0
	v_mfma_f32_16x16x32_bf16 v[54:57], v[152:155], v[196:199], v[54:57]
	v_mfma_f32_16x16x32_bf16 v[38:41], v[152:155], v[204:207], 0
	v_mfma_f32_16x16x32_bf16 v[38:41], v[156:159], v[208:211], v[38:41]
	v_mfma_f32_16x16x32_bf16 v[34:37], v[168:171], v[208:211], 0
	v_mfma_f32_16x16x32_bf16 v[34:37], v[160:163], v[204:207], v[34:37]
	v_mfma_f32_16x16x32_bf16 v[18:21], v[160:163], v[212:215], 0
	v_mfma_f32_16x16x32_bf16 v[18:21], v[168:171], v[216:219], v[18:21]
	v_mfma_f32_16x16x32_bf16 v[22:25], v[156:159], v[216:219], 0
	v_mfma_f32_16x16x32_bf16 v[22:25], v[152:155], v[212:215], v[22:25]
	v_mfma_f32_16x16x32_bf16 v[46:49], v[172:175], v[188:191], 0
	v_mfma_f32_16x16x32_bf16 v[46:49], v[176:179], v[192:195], v[46:49]
	v_mfma_f32_16x16x32_bf16 v[42:45], v[184:187], v[192:195], 0
	v_mfma_f32_16x16x32_bf16 v[42:45], v[180:183], v[188:191], v[42:45]
	v_mfma_f32_16x16x32_bf16 v[26:29], v[180:183], v[196:199], 0
	v_mfma_f32_16x16x32_bf16 v[26:29], v[184:187], v[200:203], v[26:29]
	v_mfma_f32_16x16x32_bf16 v[30:33], v[176:179], v[200:203], 0
	v_mfma_f32_16x16x32_bf16 v[30:33], v[172:175], v[196:199], v[30:33]
	v_mfma_f32_16x16x32_bf16 v[14:17], v[172:175], v[204:207], 0
	v_mfma_f32_16x16x32_bf16 v[14:17], v[176:179], v[208:211], v[14:17]
	v_mfma_f32_16x16x32_bf16 v[10:13], v[184:187], v[208:211], 0
	v_mfma_f32_16x16x32_bf16 v[10:13], v[180:183], v[204:207], v[10:13]
	v_mfma_f32_16x16x32_bf16 v[2:5], v[180:183], v[212:215], 0
	v_mfma_f32_16x16x32_bf16 v[2:5], v[184:187], v[216:219], v[2:5]
	s_setprio 2
	s_barrier
	v_mfma_f32_16x16x32_bf16 v[6:9], v[176:179], v[216:219], 0
	v_mfma_f32_16x16x32_bf16 v[6:9], v[172:175], v[212:215], v[6:9]
	s_setprio 0
	s_add_i32 s65, 0, 0x18000
	v_add_u32_e32 v151, s65, v146
	s_add_i32 s66, 0, 0x1c000
	ds_read_b128 v[152:155], v151
	ds_read_b128 v[156:159], v151 offset:1024
	ds_read_b128 v[160:163], v151 offset:2048
	ds_read_b128 v[168:171], v151 offset:3072
	v_add_u32_e32 v151, s66, v146
	ds_read_b128 v[172:175], v151
	ds_read_b128 v[176:179], v151 offset:1024
	ds_read_b128 v[180:183], v151 offset:2048
	ds_read_b128 v[184:187], v151 offset:3072
	s_add_u32 s26, s26, 0x100000
	s_addc_u32 s27, s27, 0
	s_mov_b32 m0, s31
	ds_read_b128 v[188:191], v150 offset:32768
	ds_read_b128 v[192:195], v150 offset:33792
	ds_read_b128 v[196:199], v150 offset:34816
	ds_read_b128 v[200:203], v150 offset:35840
	ds_read_b128 v[204:207], v150 offset:36864
	ds_read_b128 v[208:211], v150 offset:37888
	ds_read_b128 v[212:215], v150 offset:38912
	ds_read_b128 v[216:219], v150 offset:39936
	global_load_lds_dwordx4 v136, s[26:27]
	s_mov_b32 m0, s33
	s_nop 0
	global_load_lds_dwordx4 v132, s[26:27]
	s_waitcnt vmcnt(8)
	s_waitcnt lgkmcnt(0)
	s_barrier
	s_setprio 1
	s_waitcnt lgkmcnt(0)
	v_mfma_f32_16x16x32_bf16 v[126:129], v[152:155], v[188:191], v[126:129]
	v_mfma_f32_16x16x32_bf16 v[126:129], v[156:159], v[192:195], v[126:129]
	v_mfma_f32_16x16x32_bf16 v[122:125], v[168:171], v[192:195], v[122:125]
	v_mfma_f32_16x16x32_bf16 v[122:125], v[160:163], v[188:191], v[122:125]
	v_mfma_f32_16x16x32_bf16 v[114:117], v[160:163], v[196:199], v[114:117]
	v_mfma_f32_16x16x32_bf16 v[114:117], v[168:171], v[200:203], v[114:117]
	v_mfma_f32_16x16x32_bf16 v[118:121], v[156:159], v[200:203], v[118:121]
	v_mfma_f32_16x16x32_bf16 v[118:121], v[152:155], v[196:199], v[118:121]
	v_mfma_f32_16x16x32_bf16 v[102:105], v[152:155], v[204:207], v[102:105]
	v_mfma_f32_16x16x32_bf16 v[102:105], v[156:159], v[208:211], v[102:105]
	v_mfma_f32_16x16x32_bf16 v[98:101], v[168:171], v[208:211], v[98:101]
	v_mfma_f32_16x16x32_bf16 v[98:101], v[160:163], v[204:207], v[98:101]
	v_mfma_f32_16x16x32_bf16 v[82:85], v[160:163], v[212:215], v[82:85]
	v_mfma_f32_16x16x32_bf16 v[82:85], v[168:171], v[216:219], v[82:85]
	v_mfma_f32_16x16x32_bf16 v[86:89], v[156:159], v[216:219], v[86:89]
	v_mfma_f32_16x16x32_bf16 v[86:89], v[152:155], v[212:215], v[86:89]
	v_mfma_f32_16x16x32_bf16 v[110:113], v[172:175], v[188:191], v[110:113]
	v_mfma_f32_16x16x32_bf16 v[110:113], v[176:179], v[192:195], v[110:113]
	v_mfma_f32_16x16x32_bf16 v[106:109], v[184:187], v[192:195], v[106:109]
	v_mfma_f32_16x16x32_bf16 v[106:109], v[180:183], v[188:191], v[106:109]
	v_mfma_f32_16x16x32_bf16 v[90:93], v[180:183], v[196:199], v[90:93]
	v_mfma_f32_16x16x32_bf16 v[90:93], v[184:187], v[200:203], v[90:93]
	v_mfma_f32_16x16x32_bf16 v[94:97], v[176:179], v[200:203], v[94:97]
	v_mfma_f32_16x16x32_bf16 v[94:97], v[172:175], v[196:199], v[94:97]
	v_mfma_f32_16x16x32_bf16 v[78:81], v[172:175], v[204:207], v[78:81]
	v_mfma_f32_16x16x32_bf16 v[78:81], v[176:179], v[208:211], v[78:81]
	v_mfma_f32_16x16x32_bf16 v[74:77], v[184:187], v[208:211], v[74:77]
	v_mfma_f32_16x16x32_bf16 v[74:77], v[180:183], v[204:207], v[74:77]
	v_mfma_f32_16x16x32_bf16 v[66:69], v[180:183], v[212:215], v[66:69]
	v_mfma_f32_16x16x32_bf16 v[66:69], v[184:187], v[216:219], v[66:69]
	s_setprio 2
	s_barrier
; #define PG8_STAGE(bufoff, gbase, voff) do { _Pragma("unroll") for (int _i = 0; _i < 2; ++_i) \
;         __builtin_amdgcn_global_load_lds((const unsigned*)((const char*)(gbase) + (voff)[_i]), (PG8_LAS unsigned*)(lds + (bufoff) + ldsw + _i * 8192), 16, 0, 0); } while (0)
; #define PG8_LDA(dst, b, h) do { _Pragma("unroll") for (int m = 0; m < 4; ++m) _Pragma("unroll") for (int k = 0; k < 2; ++k) dst[m][k] = *(const PG8_LAS bf16x8*)(lds + PG8_SA(b, h) + aoff + m * 2048 + k * 1024); } while (0)
; #define PG8_MMA(ai, bj, At, Bt) do { __builtin_amdgcn_s_setprio(1); _Pragma("unroll") for (int m = 0; m < 4; ++m) _Pragma("unroll") for (int n = 0; n < 2; ++n) _Pragma("unroll") for (int k = 0; k < 2; ++k) \
;         acc[ai][bj][m][n] = __builtin_amdgcn_mfma_f32_16x16x32_bf16(Bt[n][k], At[m][k], acc[ai][bj][m][n], 0, 0, 0); __builtin_amdgcn_s_setprio(0); } while (0)
; #define PG8_WAIT_V(n) asm volatile("s_waitcnt vmcnt(" #n ")" ::: "memory")
; #define PG8_WAIT_L(n) asm volatile("s_waitcnt lgkmcnt(" #n ")" ::: "memory")
; #define PG8_BAR __builtin_amdgcn_s_barrier()
; #define PG8_SCHED __builtin_amdgcn_sched_barrier(0)
; template <class Epi, class Sched, bool ALIGN_EPI = false, bool SP2 = false>
; __device__ __forceinline__ void gemm_phase(PG8_LAS unsigned char* lds, const Gemm g, const Sched& S, const Epi& E) {
;     ...
;             PG8_LDA(At, 1, 1); PG8_STAGE(PG8_SB(1, 0), b3, voffB); PG8_STAGE(PG8_SB(1, 1), b3 + hstepB, voffB); PG8_STAGE(PG8_SA(1, 0), a3, voffA);
;             PG8_WAIT_V(8); PG8_WAIT_L(0); PG8_BAR; PG8_MMA(1, 0, At, B0); PG8_MMA(1, 1, At, B1); PG8_BAR; PG8_SCHED;
	v_mfma_f32_16x16x32_bf16 v[70:73], v[176:179], v[216:219], v[70:73]
	v_mfma_f32_16x16x32_bf16 v[70:73], v[172:175], v[212:215], v[70:73]
	s_setprio 0
	s_add_i32 s26, s65, s3
	s_mov_b32 m0, s26
	ds_read_b128 v[188:191], v150 offset:49152
	ds_read_b128 v[192:195], v150 offset:50176
	ds_read_b128 v[196:199], v150 offset:51200
	ds_read_b128 v[200:203], v150 offset:52224
	ds_read_b128 v[204:207], v150 offset:53248
	ds_read_b128 v[208:211], v150 offset:54272
	ds_read_b128 v[212:215], v150 offset:55296
	ds_read_b128 v[216:219], v150 offset:56320
	global_load_lds_dwordx4 v134, s[98:99]
	s_add_i32 m0, s26, 0x2000
	s_add_u32 s24, s24, 0x100080
	s_addc_u32 s25, s25, 0
	s_add_i32 s26, s66, s3
	global_load_lds_dwordx4 v130, s[98:99]
	s_mov_b32 m0, s26
	s_nop 0
	global_load_lds_dwordx4 v134, s[24:25]
	s_add_i32 m0, s26, 0x2000
	s_nop 0
	global_load_lds_dwordx4 v130, s[24:25]
	s_mov_b32 m0, s35
	s_nop 0
	global_load_lds_dwordx4 v136, s[100:101]
	s_mov_b32 m0, s36
	s_nop 0
	global_load_lds_dwordx4 v132, s[100:101]
	s_waitcnt vmcnt(8)
	s_waitcnt lgkmcnt(0)
	s_barrier
	s_setprio 1
	s_waitcnt lgkmcnt(0)
	v_mfma_f32_16x16x32_bf16 v[62:65], v[152:155], v[188:191], v[62:65]
	v_mfma_f32_16x16x32_bf16 v[62:65], v[156:159], v[192:195], v[62:65]
	v_mfma_f32_16x16x32_bf16 v[58:61], v[168:171], v[192:195], v[58:61]
	v_mfma_f32_16x16x32_bf16 v[58:61], v[160:163], v[188:191], v[58:61]
	v_mfma_f32_16x16x32_bf16 v[50:53], v[160:163], v[196:199], v[50:53]
	v_mfma_f32_16x16x32_bf16 v[50:53], v[168:171], v[200:203], v[50:53]
	v_mfma_f32_16x16x32_bf16 v[54:57], v[156:159], v[200:203], v[54:57]
	v_mfma_f32_16x16x32_bf16 v[54:57], v[152:155], v[196:199], v[54:57]
	v_mfma_f32_16x16x32_bf16 v[38:41], v[152:155], v[204:207], v[38:41]
	v_mfma_f32_16x16x32_bf16 v[38:41], v[156:159], v[208:211], v[38:41]
	v_mfma_f32_16x16x32_bf16 v[34:37], v[168:171], v[208:211], v[34:37]
	v_mfma_f32_16x16x32_bf16 v[34:37], v[160:163], v[204:207], v[34:37]
	v_mfma_f32_16x16x32_bf16 v[18:21], v[160:163], v[212:215], v[18:21]
	v_mfma_f32_16x16x32_bf16 v[18:21], v[168:171], v[216:219], v[18:21]
	v_mfma_f32_16x16x32_bf16 v[22:25], v[156:159], v[216:219], v[22:25]
	v_mfma_f32_16x16x32_bf16 v[22:25], v[152:155], v[212:215], v[22:25]
	v_mfma_f32_16x16x32_bf16 v[46:49], v[172:175], v[188:191], v[46:49]
	v_mfma_f32_16x16x32_bf16 v[46:49], v[176:179], v[192:195], v[46:49]
	v_mfma_f32_16x16x32_bf16 v[42:45], v[184:187], v[192:195], v[42:45]
	v_mfma_f32_16x16x32_bf16 v[42:45], v[180:183], v[188:191], v[42:45]
	v_mfma_f32_16x16x32_bf16 v[26:29], v[180:183], v[196:199], v[26:29]
	v_mfma_f32_16x16x32_bf16 v[26:29], v[184:187], v[200:203], v[26:29]
	v_mfma_f32_16x16x32_bf16 v[30:33], v[176:179], v[200:203], v[30:33]
	v_mfma_f32_16x16x32_bf16 v[30:33], v[172:175], v[196:199], v[30:33]
	v_mfma_f32_16x16x32_bf16 v[14:17], v[172:175], v[204:207], v[14:17]
	v_mfma_f32_16x16x32_bf16 v[14:17], v[176:179], v[208:211], v[14:17]
	v_mfma_f32_16x16x32_bf16 v[10:13], v[184:187], v[208:211], v[10:13]
	v_mfma_f32_16x16x32_bf16 v[10:13], v[180:183], v[204:207], v[10:13]
	v_mfma_f32_16x16x32_bf16 v[2:5], v[180:183], v[212:215], v[2:5]
	v_mfma_f32_16x16x32_bf16 v[2:5], v[184:187], v[216:219], v[2:5]
	s_setprio 2
	s_barrier
	v_mfma_f32_16x16x32_bf16 v[6:9], v[176:179], v[216:219], v[6:9]
	v_mfma_f32_16x16x32_bf16 v[6:9], v[172:175], v[212:215], v[6:9]
	s_setprio 0
	s_add_i32 s64, s64, 2
	s_add_u32 s22, s22, 0x100
	s_addc_u32 s23, s23, 0
	s_add_u32 s62, s62, 0x100
	s_addc_u32 s63, s63, 0

;     __host__ __device__ bool next(int i, Unit& u) const { const int L = i * G + c; if (L >= 4 * nM) return false; u.pm = L >> 2; u.pn = 0; u.kq = L & 3; return true; }
; #define PG8_STAGE(bufoff, gbase, voff) do { _Pragma("unroll") for (int _i = 0; _i < 2; ++_i) \
;         __builtin_amdgcn_global_load_lds((const unsigned*)((const char*)(gbase) + (voff)[_i]), (PG8_LAS unsigned*)(lds + (bufoff) + ldsw + _i * 8192), 16, 0, 0); } while (0)
; #define PG8_LDA(dst, b, h) do { _Pragma("unroll") for (int m = 0; m < 4; ++m) _Pragma("unroll") for (int k = 0; k < 2; ++k) dst[m][k] = *(const PG8_LAS bf16x8*)(lds + PG8_SA(b, h) + aoff + m * 2048 + k * 1024); } while (0)
; #define PG8_LDB(dst, b, h) do { _Pragma("unroll") for (int n = 0; n < 2; ++n) _Pragma("unroll") for (int k = 0; k < 2; ++k) dst[n][k] = *(const PG8_LAS bf16x8*)(lds + PG8_SB(b, h) + boff + n * 2048 + k * 1024); } while (0)
; template <class Epi, class Sched, bool ALIGN_EPI = false, bool SP2 = false>
; __device__ __forceinline__ void gemm_phase(PG8_LAS unsigned char* lds, const Gemm g, const Sched& S, const Epi& E) {
;     ...
;     for (;;) {
;         const bool has_next = S.next(ui + 1, nxt);
;         const char* nA = has_next ? (const char*)g.A + (size_t)nxt.pm * tstepA + nxt.kq * g.kq_bytes : cA; const char* nB = has_next ? (const char*)g.Bt + (size_t)nxt.pn * tstepB + nxt.kq * g.kq_bytes : cB;
;         for (int t = 0; t < nt; t += 2) {
;             const bool last = (t == nt - 2);
;             const char* a1 = cA + (size_t)(t + 1) * kstep + (t >= g.kj_t ? g.kj_bytes : 0);
;             const char* a2 = last ? nA : cA + (size_t)(t + 2) * kstep + (t + 2 >= g.kj_t ? g.kj_bytes : 0); const char* b2 = last ? nB : cB + (size_t)(t + 2) * kstep;
;             const char* a3 = a2 + kstep; const char* b3 = b2 + kstep;
;             if (last && has_next) S.a_ready(nxt);
;             if constexpr (Epi::MIDK) { if (t == g.kj_t) E.midk(acc, cur, wr, fr); }
;             if constexpr (SP2) {
;             PG8_LDB(B0, 0, 0); PG8_LDB(B1, 0, 1); PG8_SCHED; PG8_LDA(At, 0, 0); PG8_STAGE(PG8_SA(1, 1), a1 + hstepA, voffA);
;             PG8_WAIT_V(8); PG8_WAIT_L(0); PG8_BAR; PG8_MMA(0, 0, At, B0); PG8_MMA(0, 1, At, B1); PG8_BAR; PG8_SCHED;
;             PG8_LDA(At, 0, 1); PG8_STAGE(PG8_SB(0, 0), b2, voffB); PG8_STAGE(PG8_SB(0, 1), b2 + hstepB, voffB); PG8_STAGE(PG8_SA(0, 0), a2, voffA);
.LBB0_524:
	s_ashr_i32 s15, s14, 31
	s_lshl_b64 s[16:17], s[14:15], 21
	s_add_u32 s16, s42, s16
	s_addc_u32 s17, s43, s17
	s_and_b64 s[18:19], s[0:1], exec
	s_cselect_b32 s15, s17, s23
	s_cselect_b32 s50, s16, s22
	s_ashr_i32 s13, s12, 31
	s_lshl_b64 s[18:19], s[12:13], 21
	v_readlane_b32 s26, v253, 37
	v_readlane_b32 s27, v253, 38
	s_add_u32 s18, s26, s18
	s_addc_u32 s19, s27, s19
	s_and_b64 s[26:27], s[0:1], exec
	s_cselect_b32 s13, s19, s25
	s_cselect_b32 s51, s18, s24
	s_add_u32 s22, s22, 0x100080
	s_addc_u32 s23, s23, 0
	s_add_u32 s52, s24, 0x100
	s_addc_u32 s53, s25, 0
	s_waitcnt lgkmcnt(0)
	s_mov_b32 s60, -2
	s_waitcnt vmcnt(0)
	ds_read_b128 v[146:149], v160
	ds_read_b128 v[168:171], v160 offset:1024
	ds_read_b128 v[172:175], v160 offset:2048
	ds_read_b128 v[176:179], v160 offset:3072
	ds_read_b128 v[180:183], v161
	ds_read_b128 v[184:187], v161 offset:1024
	ds_read_b128 v[188:191], v161 offset:2048
	ds_read_b128 v[192:195], v161 offset:3072
	s_add_u32 s24, s22, 0xfff00080
	s_addc_u32 s25, s23, -1
	s_cmp_eq_u32 s60, 60
	s_cselect_b32 s27, s15, s25
	s_cselect_b32 s26, s50, s24
	s_cselect_b32 s25, s13, s53
	s_cselect_b32 s24, s51, s52
	s_add_u32 s98, s24, 0x80
	s_addc_u32 s99, s25, 0
	s_add_u32 s100, s26, 0x80
	s_addc_u32 s101, s27, 0
	s_add_i32 m0, s21, 0xc000
	ds_read_b128 v[196:199], v162
	ds_read_b128 v[200:203], v162 offset:1024
	ds_read_b128 v[204:207], v162 offset:2048
	ds_read_b128 v[208:211], v162 offset:3072
	ds_read_b128 v[212:215], v162 offset:4096
	ds_read_b128 v[216:219], v162 offset:5120
	ds_read_b128 v[220:223], v162 offset:6144
	ds_read_b128 v[224:227], v162 offset:7168
	global_load_lds_dwordx4 v138, s[22:23]
	s_add_i32 m0, s21, 0xe000
	s_nop 0
	global_load_lds_dwordx4 v140, s[22:23]
	s_waitcnt vmcnt(8)
	s_waitcnt lgkmcnt(0)
	s_barrier
	s_setprio 1
	s_waitcnt lgkmcnt(0)
	v_mfma_f32_16x16x32_bf16 v[126:129], v[146:149], v[196:199], 0
	v_mfma_f32_16x16x32_bf16 v[126:129], v[168:171], v[200:203], v[126:129]
	v_mfma_f32_16x16x32_bf16 v[122:125], v[176:179], v[200:203], 0
	v_mfma_f32_16x16x32_bf16 v[122:125], v[172:175], v[196:199], v[122:125]
	v_mfma_f32_16x16x32_bf16 v[114:117], v[172:175], v[204:207], 0
	v_mfma_f32_16x16x32_bf16 v[114:117], v[176:179], v[208:211], v[114:117]
	v_mfma_f32_16x16x32_bf16 v[118:121], v[168:171], v[208:211], 0
	v_mfma_f32_16x16x32_bf16 v[118:121], v[146:149], v[204:207], v[118:121]
	v_mfma_f32_16x16x32_bf16 v[110:113], v[146:149], v[212:215], 0
	v_mfma_f32_16x16x32_bf16 v[110:113], v[168:171], v[216:219], v[110:113]
	v_mfma_f32_16x16x32_bf16 v[98:101], v[176:179], v[216:219], 0
	v_mfma_f32_16x16x32_bf16 v[98:101], v[172:175], v[212:215], v[98:101]
	v_mfma_f32_16x16x32_bf16 v[78:81], v[172:175], v[220:223], 0
	v_mfma_f32_16x16x32_bf16 v[78:81], v[176:179], v[224:227], v[78:81]
	v_mfma_f32_16x16x32_bf16 v[82:85], v[168:171], v[224:227], 0
	v_mfma_f32_16x16x32_bf16 v[82:85], v[146:149], v[220:223], v[82:85]
	v_mfma_f32_16x16x32_bf16 v[106:109], v[180:183], v[196:199], 0
	v_mfma_f32_16x16x32_bf16 v[106:109], v[184:187], v[200:203], v[106:109]
	v_mfma_f32_16x16x32_bf16 v[102:105], v[192:195], v[200:203], 0
	v_mfma_f32_16x16x32_bf16 v[102:105], v[188:191], v[196:199], v[102:105]
	v_mfma_f32_16x16x32_bf16 v[90:93], v[188:191], v[204:207], 0
	v_mfma_f32_16x16x32_bf16 v[90:93], v[192:195], v[208:211], v[90:93]
	v_mfma_f32_16x16x32_bf16 v[94:97], v[184:187], v[208:211], 0
	v_mfma_f32_16x16x32_bf16 v[94:97], v[180:183], v[204:207], v[94:97]
	v_mfma_f32_16x16x32_bf16 v[86:89], v[180:183], v[212:215], 0
	v_mfma_f32_16x16x32_bf16 v[86:89], v[184:187], v[216:219], v[86:89]
	v_mfma_f32_16x16x32_bf16 v[74:77], v[192:195], v[216:219], 0
	v_mfma_f32_16x16x32_bf16 v[74:77], v[188:191], v[212:215], v[74:77]
	v_mfma_f32_16x16x32_bf16 v[66:69], v[188:191], v[220:223], 0
	v_mfma_f32_16x16x32_bf16 v[66:69], v[192:195], v[224:227], v[66:69]
	s_setprio 2
	s_barrier
	v_mfma_f32_16x16x32_bf16 v[70:73], v[184:187], v[224:227], 0
	v_mfma_f32_16x16x32_bf16 v[70:73], v[180:183], v[220:223], v[70:73]
	s_setprio 0
	s_add_i32 s61, s38, s3
	s_mov_b32 m0, s61
	ds_read_b128 v[196:199], v162 offset:16384
	ds_read_b128 v[200:203], v162 offset:17408
	ds_read_b128 v[204:207], v162 offset:18432
	ds_read_b128 v[208:211], v162 offset:19456
	ds_read_b128 v[212:215], v162 offset:20480
	ds_read_b128 v[216:219], v162 offset:21504
	ds_read_b128 v[220:223], v162 offset:22528
	ds_read_b128 v[224:227], v162 offset:23552
	global_load_lds_dwordx4 v136, s[24:25]
	s_add_i32 m0, s61, 0x2000
	s_add_u32 s62, s24, 0x100000
	s_addc_u32 s63, s25, 0
	s_add_i32 s61, s39, s3
	global_load_lds_dwordx4 v134, s[24:25]
	s_mov_b32 m0, s61
	s_nop 0
	global_load_lds_dwordx4 v136, s[62:63]
	s_add_i32 m0, s61, 0x2000
	s_nop 0
	global_load_lds_dwordx4 v134, s[62:63]
	s_mov_b32 m0, s21
	s_nop 0
	global_load_lds_dwordx4 v130, s[26:27]
	s_mov_b32 m0, s30
	s_nop 0
	global_load_lds_dwordx4 v132, s[26:27]
	s_waitcnt vmcnt(8)
	s_waitcnt lgkmcnt(0)
	s_barrier
; #define PG8_STAGE(bufoff, gbase, voff) do { _Pragma("unroll") for (int _i = 0; _i < 2; ++_i) \
;         __builtin_amdgcn_global_load_lds((const unsigned*)((const char*)(gbase) + (voff)[_i]), (PG8_LAS unsigned*)(lds + (bufoff) + ldsw + _i * 8192), 16, 0, 0); } while (0)
; #define PG8_LDA(dst, b, h) do { _Pragma("unroll") for (int m = 0; m < 4; ++m) _Pragma("unroll") for (int k = 0; k < 2; ++k) dst[m][k] = *(const PG8_LAS bf16x8*)(lds + PG8_SA(b, h) + aoff + m * 2048 + k * 1024); } while (0)
; #define PG8_LDB(dst, b, h) do { _Pragma("unroll") for (int n = 0; n < 2; ++n) _Pragma("unroll") for (int k = 0; k < 2; ++k) dst[n][k] = *(const PG8_LAS bf16x8*)(lds + PG8_SB(b, h) + boff + n * 2048 + k * 1024); } while (0)
; #define PG8_MMA(ai, bj, At, Bt) do { __builtin_amdgcn_s_setprio(1); _Pragma("unroll") for (int m = 0; m < 4; ++m) _Pragma("unroll") for (int n = 0; n < 2; ++n) _Pragma("unroll") for (int k = 0; k < 2; ++k) \
;         acc[ai][bj][m][n] = __builtin_amdgcn_mfma_f32_16x16x32_bf16(Bt[n][k], At[m][k], acc[ai][bj][m][n], 0, 0, 0); __builtin_amdgcn_s_setprio(0); } while (0)
; #define PG8_WAIT_V(n) asm volatile("s_waitcnt vmcnt(" #n ")" ::: "memory")
; #define PG8_WAIT_L(n) asm volatile("s_waitcnt lgkmcnt(" #n ")" ::: "memory")
; #define PG8_BAR __builtin_amdgcn_s_barrier()
; #define PG8_SCHED __builtin_amdgcn_sched_barrier(0)
; template <class Epi, class Sched, bool ALIGN_EPI = false, bool SP2 = false>
; __device__ __forceinline__ void gemm_phase(PG8_LAS unsigned char* lds, const Gemm g, const Sched& S, const Epi& E) {
;     ...
;             PG8_WAIT_V(8); PG8_WAIT_L(0); PG8_BAR; PG8_MMA(1, 0, At, B0); PG8_MMA(1, 1, At, B1); PG8_BAR; PG8_SCHED;
;             PG8_LDB(B0, 1, 0); PG8_LDB(B1, 1, 1); PG8_SCHED; PG8_LDA(At, 1, 0); PG8_STAGE(PG8_SA(0, 1), a2 + hstepA, voffA);
;             PG8_WAIT_V(8); PG8_WAIT_L(0); PG8_BAR; PG8_MMA(0, 0, At, B0); PG8_MMA(0, 1, At, B1); PG8_BAR; PG8_SCHED;
;             PG8_LDA(At, 1, 1); PG8_STAGE(PG8_SB(1, 0), b3, voffB); PG8_STAGE(PG8_SB(1, 1), b3 + hstepB, voffB); PG8_STAGE(PG8_SA(1, 0), a3, voffA);
	s_setprio 1
	s_waitcnt lgkmcnt(0)
	v_mfma_f32_16x16x32_bf16 v[62:65], v[146:149], v[196:199], 0
	v_mfma_f32_16x16x32_bf16 v[62:65], v[168:171], v[200:203], v[62:65]
	v_mfma_f32_16x16x32_bf16 v[58:61], v[176:179], v[200:203], 0
	v_mfma_f32_16x16x32_bf16 v[58:61], v[172:175], v[196:199], v[58:61]
	v_mfma_f32_16x16x32_bf16 v[46:49], v[172:175], v[204:207], 0
	v_mfma_f32_16x16x32_bf16 v[46:49], v[176:179], v[208:211], v[46:49]
	v_mfma_f32_16x16x32_bf16 v[54:57], v[168:171], v[208:211], 0
	v_mfma_f32_16x16x32_bf16 v[54:57], v[146:149], v[204:207], v[54:57]
	v_mfma_f32_16x16x32_bf16 v[38:41], v[146:149], v[212:215], 0
	v_mfma_f32_16x16x32_bf16 v[38:41], v[168:171], v[216:219], v[38:41]
	v_mfma_f32_16x16x32_bf16 v[30:33], v[176:179], v[216:219], 0
	v_mfma_f32_16x16x32_bf16 v[30:33], v[172:175], v[212:215], v[30:33]
	v_mfma_f32_16x16x32_bf16 v[14:17], v[172:175], v[220:223], 0
	v_mfma_f32_16x16x32_bf16 v[14:17], v[176:179], v[224:227], v[14:17]
	v_mfma_f32_16x16x32_bf16 v[22:25], v[168:171], v[224:227], 0
	v_mfma_f32_16x16x32_bf16 v[22:25], v[146:149], v[220:223], v[22:25]
	v_mfma_f32_16x16x32_bf16 v[50:53], v[180:183], v[196:199], 0
	v_mfma_f32_16x16x32_bf16 v[50:53], v[184:187], v[200:203], v[50:53]
	v_mfma_f32_16x16x32_bf16 v[42:45], v[192:195], v[200:203], 0
	v_mfma_f32_16x16x32_bf16 v[42:45], v[188:191], v[196:199], v[42:45]
	v_mfma_f32_16x16x32_bf16 v[26:29], v[188:191], v[204:207], 0
	v_mfma_f32_16x16x32_bf16 v[26:29], v[192:195], v[208:211], v[26:29]
	v_mfma_f32_16x16x32_bf16 v[34:37], v[184:187], v[208:211], 0
	v_mfma_f32_16x16x32_bf16 v[34:37], v[180:183], v[204:207], v[34:37]
	v_mfma_f32_16x16x32_bf16 v[18:21], v[180:183], v[212:215], 0
	v_mfma_f32_16x16x32_bf16 v[18:21], v[184:187], v[216:219], v[18:21]
	v_mfma_f32_16x16x32_bf16 v[10:13], v[192:195], v[216:219], 0
	v_mfma_f32_16x16x32_bf16 v[10:13], v[188:191], v[212:215], v[10:13]
	v_mfma_f32_16x16x32_bf16 v[2:5], v[188:191], v[220:223], 0
	v_mfma_f32_16x16x32_bf16 v[2:5], v[192:195], v[224:227], v[2:5]
	s_setprio 2
	s_barrier
	v_mfma_f32_16x16x32_bf16 v[6:9], v[184:187], v[224:227], 0
	v_mfma_f32_16x16x32_bf16 v[6:9], v[180:183], v[220:223], v[6:9]
	s_setprio 0
	s_add_i32 s61, 0, 0x18000
	v_add_u32_e32 v150, s61, v158
	s_add_i32 s62, 0, 0x1c000
	ds_read_b128 v[146:149], v150
	ds_read_b128 v[168:171], v150 offset:1024
	ds_read_b128 v[172:175], v150 offset:2048
	ds_read_b128 v[176:179], v150 offset:3072
	v_add_u32_e32 v150, s62, v158
	ds_read_b128 v[180:183], v150
	ds_read_b128 v[184:187], v150 offset:1024
	ds_read_b128 v[188:191], v150 offset:2048
	ds_read_b128 v[192:195], v150 offset:3072
	s_add_u32 s26, s26, 0x100000
	s_addc_u32 s27, s27, 0
	s_mov_b32 m0, s31
	ds_read_b128 v[196:199], v162 offset:32768
	ds_read_b128 v[200:203], v162 offset:33792
	ds_read_b128 v[204:207], v162 offset:34816
	ds_read_b128 v[208:211], v162 offset:35840
	ds_read_b128 v[212:215], v162 offset:36864
	ds_read_b128 v[216:219], v162 offset:37888
	ds_read_b128 v[220:223], v162 offset:38912
	ds_read_b128 v[224:227], v162 offset:39936
	global_load_lds_dwordx4 v130, s[26:27]
	s_mov_b32 m0, s33
	s_nop 0
	global_load_lds_dwordx4 v132, s[26:27]
	s_waitcnt vmcnt(8)
	s_waitcnt lgkmcnt(0)
	s_barrier
	s_setprio 1
	s_waitcnt lgkmcnt(0)
	v_mfma_f32_16x16x32_bf16 v[126:129], v[146:149], v[196:199], v[126:129]
	v_mfma_f32_16x16x32_bf16 v[126:129], v[168:171], v[200:203], v[126:129]
	v_mfma_f32_16x16x32_bf16 v[122:125], v[176:179], v[200:203], v[122:125]
	v_mfma_f32_16x16x32_bf16 v[122:125], v[172:175], v[196:199], v[122:125]
	v_mfma_f32_16x16x32_bf16 v[114:117], v[172:175], v[204:207], v[114:117]
	v_mfma_f32_16x16x32_bf16 v[114:117], v[176:179], v[208:211], v[114:117]
	v_mfma_f32_16x16x32_bf16 v[118:121], v[168:171], v[208:211], v[118:121]
	v_mfma_f32_16x16x32_bf16 v[118:121], v[146:149], v[204:207], v[118:121]
	v_mfma_f32_16x16x32_bf16 v[110:113], v[146:149], v[212:215], v[110:113]
	v_mfma_f32_16x16x32_bf16 v[110:113], v[168:171], v[216:219], v[110:113]
	v_mfma_f32_16x16x32_bf16 v[98:101], v[176:179], v[216:219], v[98:101]
	v_mfma_f32_16x16x32_bf16 v[98:101], v[172:175], v[212:215], v[98:101]
	v_mfma_f32_16x16x32_bf16 v[78:81], v[172:175], v[220:223], v[78:81]
	v_mfma_f32_16x16x32_bf16 v[78:81], v[176:179], v[224:227], v[78:81]
	v_mfma_f32_16x16x32_bf16 v[82:85], v[168:171], v[224:227], v[82:85]
	v_mfma_f32_16x16x32_bf16 v[82:85], v[146:149], v[220:223], v[82:85]
	v_mfma_f32_16x16x32_bf16 v[106:109], v[180:183], v[196:199], v[106:109]
	v_mfma_f32_16x16x32_bf16 v[106:109], v[184:187], v[200:203], v[106:109]
	v_mfma_f32_16x16x32_bf16 v[102:105], v[192:195], v[200:203], v[102:105]
	v_mfma_f32_16x16x32_bf16 v[102:105], v[188:191], v[196:199], v[102:105]
	v_mfma_f32_16x16x32_bf16 v[90:93], v[188:191], v[204:207], v[90:93]
	v_mfma_f32_16x16x32_bf16 v[90:93], v[192:195], v[208:211], v[90:93]
	v_mfma_f32_16x16x32_bf16 v[94:97], v[184:187], v[208:211], v[94:97]
	v_mfma_f32_16x16x32_bf16 v[94:97], v[180:183], v[204:207], v[94:97]
	v_mfma_f32_16x16x32_bf16 v[86:89], v[180:183], v[212:215], v[86:89]
	v_mfma_f32_16x16x32_bf16 v[86:89], v[184:187], v[216:219], v[86:89]
	v_mfma_f32_16x16x32_bf16 v[74:77], v[192:195], v[216:219], v[74:77]
	v_mfma_f32_16x16x32_bf16 v[74:77], v[188:191], v[212:215], v[74:77]
	v_mfma_f32_16x16x32_bf16 v[66:69], v[188:191], v[220:223], v[66:69]
	v_mfma_f32_16x16x32_bf16 v[66:69], v[192:195], v[224:227], v[66:69]
	s_setprio 2
	s_barrier
; #define PG8_STAGE(bufoff, gbase, voff) do { _Pragma("unroll") for (int _i = 0; _i < 2; ++_i) \
;         __builtin_amdgcn_global_load_lds((const unsigned*)((const char*)(gbase) + (voff)[_i]), (PG8_LAS unsigned*)(lds + (bufoff) + ldsw + _i * 8192), 16, 0, 0); } while (0)
; #define PG8_LDA(dst, b, h) do { _Pragma("unroll") for (int m = 0; m < 4; ++m) _Pragma("unroll") for (int k = 0; k < 2; ++k) dst[m][k] = *(const PG8_LAS bf16x8*)(lds + PG8_SA(b, h) + aoff + m * 2048 + k * 1024); } while (0)
; #define PG8_MMA(ai, bj, At, Bt) do { __builtin_amdgcn_s_setprio(1); _Pragma("unroll") for (int m = 0; m < 4; ++m) _Pragma("unroll") for (int n = 0; n < 2; ++n) _Pragma("unroll") for (int k = 0; k < 2; ++k) \
;         acc[ai][bj][m][n] = __builtin_amdgcn_mfma_f32_16x16x32_bf16(Bt[n][k], At[m][k], acc[ai][bj][m][n], 0, 0, 0); __builtin_amdgcn_s_setprio(0); } while (0)
; #define PG8_WAIT_V(n) asm volatile("s_waitcnt vmcnt(" #n ")" ::: "memory")
; #define PG8_WAIT_L(n) asm volatile("s_waitcnt lgkmcnt(" #n ")" ::: "memory")
; #define PG8_BAR __builtin_amdgcn_s_barrier()
; #define PG8_SCHED __builtin_amdgcn_sched_barrier(0)
; template <class Epi, class Sched, bool ALIGN_EPI = false, bool SP2 = false>
; __device__ __forceinline__ void gemm_phase(PG8_LAS unsigned char* lds, const Gemm g, const Sched& S, const Epi& E) {
;     ...
;             PG8_LDA(At, 1, 1); PG8_STAGE(PG8_SB(1, 0), b3, voffB); PG8_STAGE(PG8_SB(1, 1), b3 + hstepB, voffB); PG8_STAGE(PG8_SA(1, 0), a3, voffA);
;             PG8_WAIT_V(8); PG8_WAIT_L(0); PG8_BAR; PG8_MMA(1, 0, At, B0); PG8_MMA(1, 1, At, B1); PG8_BAR; PG8_SCHED;
	v_mfma_f32_16x16x32_bf16 v[70:73], v[184:187], v[224:227], v[70:73]
	v_mfma_f32_16x16x32_bf16 v[70:73], v[180:183], v[220:223], v[70:73]
	s_setprio 0
	s_add_i32 s26, s61, s3
	s_mov_b32 m0, s26
	ds_read_b128 v[196:199], v162 offset:49152
	ds_read_b128 v[200:203], v162 offset:50176
	ds_read_b128 v[204:207], v162 offset:51200
	ds_read_b128 v[208:211], v162 offset:52224
	ds_read_b128 v[212:215], v162 offset:53248
	ds_read_b128 v[216:219], v162 offset:54272
	ds_read_b128 v[220:223], v162 offset:55296
	ds_read_b128 v[224:227], v162 offset:56320
	global_load_lds_dwordx4 v136, s[98:99]
	s_add_i32 m0, s26, 0x2000
	s_add_u32 s24, s24, 0x100080
	s_addc_u32 s25, s25, 0
	s_add_i32 s26, s62, s3
	global_load_lds_dwordx4 v134, s[98:99]
	s_mov_b32 m0, s26
	s_nop 0
	global_load_lds_dwordx4 v136, s[24:25]
	s_add_i32 m0, s26, 0x2000
	s_nop 0
	global_load_lds_dwordx4 v134, s[24:25]
	s_mov_b32 m0, s35
	s_nop 0
	global_load_lds_dwordx4 v130, s[100:101]
	s_mov_b32 m0, s36
	s_nop 0
	global_load_lds_dwordx4 v132, s[100:101]
	s_waitcnt vmcnt(8)
	s_waitcnt lgkmcnt(0)
	s_barrier
	s_setprio 1
	s_waitcnt lgkmcnt(0)
	v_mfma_f32_16x16x32_bf16 v[62:65], v[146:149], v[196:199], v[62:65]
	v_mfma_f32_16x16x32_bf16 v[62:65], v[168:171], v[200:203], v[62:65]
	v_mfma_f32_16x16x32_bf16 v[58:61], v[176:179], v[200:203], v[58:61]
	v_mfma_f32_16x16x32_bf16 v[58:61], v[172:175], v[196:199], v[58:61]
	v_mfma_f32_16x16x32_bf16 v[46:49], v[172:175], v[204:207], v[46:49]
	v_mfma_f32_16x16x32_bf16 v[46:49], v[176:179], v[208:211], v[46:49]
	v_mfma_f32_16x16x32_bf16 v[54:57], v[168:171], v[208:211], v[54:57]
	v_mfma_f32_16x16x32_bf16 v[54:57], v[146:149], v[204:207], v[54:57]
	v_mfma_f32_16x16x32_bf16 v[38:41], v[146:149], v[212:215], v[38:41]
	v_mfma_f32_16x16x32_bf16 v[38:41], v[168:171], v[216:219], v[38:41]
	v_mfma_f32_16x16x32_bf16 v[30:33], v[176:179], v[216:219], v[30:33]
	v_mfma_f32_16x16x32_bf16 v[30:33], v[172:175], v[212:215], v[30:33]
	v_mfma_f32_16x16x32_bf16 v[14:17], v[172:175], v[220:223], v[14:17]
	v_mfma_f32_16x16x32_bf16 v[14:17], v[176:179], v[224:227], v[14:17]
	v_mfma_f32_16x16x32_bf16 v[22:25], v[168:171], v[224:227], v[22:25]
	v_mfma_f32_16x16x32_bf16 v[22:25], v[146:149], v[220:223], v[22:25]
	v_mfma_f32_16x16x32_bf16 v[50:53], v[180:183], v[196:199], v[50:53]
	v_mfma_f32_16x16x32_bf16 v[50:53], v[184:187], v[200:203], v[50:53]
	v_mfma_f32_16x16x32_bf16 v[42:45], v[192:195], v[200:203], v[42:45]
	v_mfma_f32_16x16x32_bf16 v[42:45], v[188:191], v[196:199], v[42:45]
	v_mfma_f32_16x16x32_bf16 v[26:29], v[188:191], v[204:207], v[26:29]
	v_mfma_f32_16x16x32_bf16 v[26:29], v[192:195], v[208:211], v[26:29]
	v_mfma_f32_16x16x32_bf16 v[34:37], v[184:187], v[208:211], v[34:37]
	v_mfma_f32_16x16x32_bf16 v[34:37], v[180:183], v[204:207], v[34:37]
	v_mfma_f32_16x16x32_bf16 v[18:21], v[180:183], v[212:215], v[18:21]
	v_mfma_f32_16x16x32_bf16 v[18:21], v[184:187], v[216:219], v[18:21]
	v_mfma_f32_16x16x32_bf16 v[10:13], v[192:195], v[216:219], v[10:13]
	v_mfma_f32_16x16x32_bf16 v[10:13], v[188:191], v[212:215], v[10:13]
	v_mfma_f32_16x16x32_bf16 v[2:5], v[188:191], v[220:223], v[2:5]
	v_mfma_f32_16x16x32_bf16 v[2:5], v[192:195], v[224:227], v[2:5]
	s_setprio 2
	s_barrier
	v_mfma_f32_16x16x32_bf16 v[6:9], v[184:187], v[224:227], v[6:9]
	v_mfma_f32_16x16x32_bf16 v[6:9], v[180:183], v[220:223], v[6:9]
	s_setprio 0
	s_add_i32 s60, s60, 2
	s_add_u32 s22, s22, 0x100
	s_addc_u32 s23, s23, 0
	s_add_u32 s52, s52, 0x100
	s_addc_u32 s53, s53, 0

;     __host__ __device__ bool next(int i, Unit& u) const { const int L = i * G + c; if (L >= 4 * nM) return false; u.pm = L >> 2; u.pn = 0; u.kq = L & 3; return true; }
; #define PG8_STAGE(bufoff, gbase, voff) do { _Pragma("unroll") for (int _i = 0; _i < 2; ++_i) \
;         __builtin_amdgcn_global_load_lds((const unsigned*)((const char*)(gbase) + (voff)[_i]), (PG8_LAS unsigned*)(lds + (bufoff) + ldsw + _i * 8192), 16, 0, 0); } while (0)
; #define PG8_LDA(dst, b, h) do { _Pragma("unroll") for (int m = 0; m < 4; ++m) _Pragma("unroll") for (int k = 0; k < 2; ++k) dst[m][k] = *(const PG8_LAS bf16x8*)(lds + PG8_SA(b, h) + aoff + m * 2048 + k * 1024); } while (0)
; #define PG8_LDB(dst, b, h) do { _Pragma("unroll") for (int n = 0; n < 2; ++n) _Pragma("unroll") for (int k = 0; k < 2; ++k) dst[n][k] = *(const PG8_LAS bf16x8*)(lds + PG8_SB(b, h) + boff + n * 2048 + k * 1024); } while (0)
; template <class Epi, class Sched, bool ALIGN_EPI = false, bool SP2 = false>
; __device__ __forceinline__ void gemm_phase(PG8_LAS unsigned char* lds, const Gemm g, const Sched& S, const Epi& E) {
;     ...
;     for (;;) {
;         const bool has_next = S.next(ui + 1, nxt);
;         const char* nA = has_next ? (const char*)g.A + (size_t)nxt.pm * tstepA + nxt.kq * g.kq_bytes : cA; const char* nB = has_next ? (const char*)g.Bt + (size_t)nxt.pn * tstepB + nxt.kq * g.kq_bytes : cB;
;         for (int t = 0; t < nt; t += 2) {
;             const bool last = (t == nt - 2);
;             const char* a1 = cA + (size_t)(t + 1) * kstep + (t >= g.kj_t ? g.kj_bytes : 0);
;             const char* a2 = last ? nA : cA + (size_t)(t + 2) * kstep + (t + 2 >= g.kj_t ? g.kj_bytes : 0); const char* b2 = last ? nB : cB + (size_t)(t + 2) * kstep;
;             const char* a3 = a2 + kstep; const char* b3 = b2 + kstep;
;             if (last && has_next) S.a_ready(nxt);
;             if constexpr (Epi::MIDK) { if (t == g.kj_t) E.midk(acc, cur, wr, fr); }
;             if constexpr (SP2) {
;             PG8_LDB(B0, 0, 0); PG8_LDB(B1, 0, 1); PG8_SCHED; PG8_LDA(At, 0, 0); PG8_STAGE(PG8_SA(1, 1), a1 + hstepA, voffA);
;             PG8_WAIT_V(8); PG8_WAIT_L(0); PG8_BAR; PG8_MMA(0, 0, At, B0); PG8_MMA(0, 1, At, B1); PG8_BAR; PG8_SCHED;
;             PG8_LDA(At, 0, 1); PG8_STAGE(PG8_SB(0, 0), b2, voffB); PG8_STAGE(PG8_SB(0, 1), b2 + hstepB, voffB); PG8_STAGE(PG8_SA(0, 0), a2, voffA);
.LBB0_881:
	s_ashr_i32 s27, s26, 31
	s_lshl_b64 s[30:31], s[26:27], 22
	v_readlane_b32 s64, v253, 39
	v_readlane_b32 s65, v253, 40
	s_add_u32 s30, s64, s30
	s_addc_u32 s31, s65, s31
	s_and_b64 s[6:7], s[6:7], exec
	s_cselect_b32 s27, s31, s37
	s_cselect_b32 s35, s30, s36
	s_add_u32 s6, s38, 0x490080
	s_addc_u32 s7, s39, 0
	s_add_u32 s63, s36, 0x100
	s_addc_u32 s64, s37, 0
	s_mov_b32 s65, -2
	ds_read_b128 v[128:131], v192
	ds_read_b128 v[132:135], v192 offset:1024
	ds_read_b128 v[136:139], v192 offset:2048
	ds_read_b128 v[140:143], v192 offset:3072
	ds_read_b128 v[160:163], v193
	ds_read_b128 v[168:171], v193 offset:1024
	ds_read_b128 v[172:175], v193 offset:2048
	ds_read_b128 v[176:179], v193 offset:3072
	s_add_u32 s36, s6, 0xffb70080
	s_addc_u32 s37, s7, -1
	s_cmpk_eq_i32 s65, 0x7c
	s_cselect_b32 s39, s29, s37
	s_cselect_b32 s38, s28, s36
	s_cselect_b32 s37, s27, s64
	s_cselect_b32 s36, s35, s63
	s_add_u32 s98, s36, 0x80
	s_addc_u32 s99, s37, 0
	s_add_u32 s100, s38, 0x80
	s_addc_u32 s101, s39, 0
	s_add_i32 m0, s41, 0xc000
	ds_read_b128 v[180:183], v194
	ds_read_b128 v[184:187], v194 offset:1024
	ds_read_b128 v[196:199], v194 offset:2048
	ds_read_b128 v[200:203], v194 offset:3072
	ds_read_b128 v[204:207], v194 offset:4096
	ds_read_b128 v[208:211], v194 offset:5120
	ds_read_b128 v[212:215], v194 offset:6144
	ds_read_b128 v[216:219], v194 offset:7168
	global_load_lds_dwordx4 v152, s[6:7]
	s_add_i32 m0, s41, 0xe000
	s_nop 0
	global_load_lds_dwordx4 v154, s[6:7]
	s_waitcnt vmcnt(8)
	s_waitcnt lgkmcnt(0)
	s_barrier
	s_setprio 1
	s_waitcnt lgkmcnt(0)
	v_mfma_f32_16x16x32_bf16 v[124:127], v[128:131], v[180:183], 0
	v_mfma_f32_16x16x32_bf16 v[124:127], v[132:135], v[184:187], v[124:127]
	v_mfma_f32_16x16x32_bf16 v[120:123], v[140:143], v[184:187], 0
	v_mfma_f32_16x16x32_bf16 v[120:123], v[136:139], v[180:183], v[120:123]
	v_mfma_f32_16x16x32_bf16 v[104:107], v[136:139], v[196:199], 0
	v_mfma_f32_16x16x32_bf16 v[104:107], v[140:143], v[200:203], v[104:107]
	v_mfma_f32_16x16x32_bf16 v[108:111], v[132:135], v[200:203], 0
	v_mfma_f32_16x16x32_bf16 v[108:111], v[128:131], v[196:199], v[108:111]
	v_mfma_f32_16x16x32_bf16 v[92:95], v[128:131], v[204:207], 0
	v_mfma_f32_16x16x32_bf16 v[92:95], v[132:135], v[208:211], v[92:95]
	v_mfma_f32_16x16x32_bf16 v[88:91], v[140:143], v[208:211], 0
	v_mfma_f32_16x16x32_bf16 v[88:91], v[136:139], v[204:207], v[88:91]
	v_mfma_f32_16x16x32_bf16 v[72:75], v[136:139], v[212:215], 0
	v_mfma_f32_16x16x32_bf16 v[72:75], v[140:143], v[216:219], v[72:75]
	v_mfma_f32_16x16x32_bf16 v[76:79], v[132:135], v[216:219], 0
	v_mfma_f32_16x16x32_bf16 v[76:79], v[128:131], v[212:215], v[76:79]
	v_mfma_f32_16x16x32_bf16 v[116:119], v[160:163], v[180:183], 0
	v_mfma_f32_16x16x32_bf16 v[116:119], v[168:171], v[184:187], v[116:119]
	v_mfma_f32_16x16x32_bf16 v[112:115], v[176:179], v[184:187], 0
	v_mfma_f32_16x16x32_bf16 v[112:115], v[172:175], v[180:183], v[112:115]
	v_mfma_f32_16x16x32_bf16 v[96:99], v[172:175], v[196:199], 0
	v_mfma_f32_16x16x32_bf16 v[96:99], v[176:179], v[200:203], v[96:99]
	v_mfma_f32_16x16x32_bf16 v[100:103], v[168:171], v[200:203], 0
	v_mfma_f32_16x16x32_bf16 v[100:103], v[160:163], v[196:199], v[100:103]
	v_mfma_f32_16x16x32_bf16 v[84:87], v[160:163], v[204:207], 0
	v_mfma_f32_16x16x32_bf16 v[84:87], v[168:171], v[208:211], v[84:87]
	v_mfma_f32_16x16x32_bf16 v[80:83], v[176:179], v[208:211], 0
	v_mfma_f32_16x16x32_bf16 v[80:83], v[172:175], v[204:207], v[80:83]
	v_mfma_f32_16x16x32_bf16 v[64:67], v[172:175], v[212:215], 0
	v_mfma_f32_16x16x32_bf16 v[64:67], v[176:179], v[216:219], v[64:67]
	s_setprio 2
	s_barrier
	v_mfma_f32_16x16x32_bf16 v[68:71], v[168:171], v[216:219], 0
	v_mfma_f32_16x16x32_bf16 v[68:71], v[160:163], v[212:215], v[68:71]
	s_setprio 0
	s_add_i32 s66, s52, s40
	s_mov_b32 m0, s66
	ds_read_b128 v[180:183], v194 offset:16384
	ds_read_b128 v[184:187], v194 offset:17408
	ds_read_b128 v[196:199], v194 offset:18432
	ds_read_b128 v[200:203], v194 offset:19456
	ds_read_b128 v[204:207], v194 offset:20480
	ds_read_b128 v[208:211], v194 offset:21504
	ds_read_b128 v[212:215], v194 offset:22528
	ds_read_b128 v[216:219], v194 offset:23552
	global_load_lds_dwordx4 v146, s[36:37]
	s_add_i32 m0, s66, 0x2000
	s_add_u32 s66, s36, 0x200000
	s_addc_u32 s67, s37, 0
	s_add_i32 s68, s53, s40
	global_load_lds_dwordx4 v150, s[36:37]
	s_mov_b32 m0, s68
	s_nop 0
	global_load_lds_dwordx4 v146, s[66:67]
	s_add_i32 m0, s68, 0x2000
	s_nop 0
	global_load_lds_dwordx4 v150, s[66:67]
	s_mov_b32 m0, s41
	s_nop 0
	global_load_lds_dwordx4 v144, s[38:39]
	s_mov_b32 m0, s44
	s_nop 0
	global_load_lds_dwordx4 v148, s[38:39]
	s_waitcnt vmcnt(8)
	s_waitcnt lgkmcnt(0)
	s_barrier
; #define PG8_STAGE(bufoff, gbase, voff) do { _Pragma("unroll") for (int _i = 0; _i < 2; ++_i) \
;         __builtin_amdgcn_global_load_lds((const unsigned*)((const char*)(gbase) + (voff)[_i]), (PG8_LAS unsigned*)(lds + (bufoff) + ldsw + _i * 8192), 16, 0, 0); } while (0)
; #define PG8_LDA(dst, b, h) do { _Pragma("unroll") for (int m = 0; m < 4; ++m) _Pragma("unroll") for (int k = 0; k < 2; ++k) dst[m][k] = *(const PG8_LAS bf16x8*)(lds + PG8_SA(b, h) + aoff + m * 2048 + k * 1024); } while (0)
; #define PG8_LDB(dst, b, h) do { _Pragma("unroll") for (int n = 0; n < 2; ++n) _Pragma("unroll") for (int k = 0; k < 2; ++k) dst[n][k] = *(const PG8_LAS bf16x8*)(lds + PG8_SB(b, h) + boff + n * 2048 + k * 1024); } while (0)
; #define PG8_MMA(ai, bj, At, Bt) do { __builtin_amdgcn_s_setprio(1); _Pragma("unroll") for (int m = 0; m < 4; ++m) _Pragma("unroll") for (int n = 0; n < 2; ++n) _Pragma("unroll") for (int k = 0; k < 2; ++k) \
;         acc[ai][bj][m][n] = __builtin_amdgcn_mfma_f32_16x16x32_bf16(Bt[n][k], At[m][k], acc[ai][bj][m][n], 0, 0, 0); __builtin_amdgcn_s_setprio(0); } while (0)
; #define PG8_WAIT_V(n) asm volatile("s_waitcnt vmcnt(" #n ")" ::: "memory")
; #define PG8_WAIT_L(n) asm volatile("s_waitcnt lgkmcnt(" #n ")" ::: "memory")
; #define PG8_BAR __builtin_amdgcn_s_barrier()
; #define PG8_SCHED __builtin_amdgcn_sched_barrier(0)
; template <class Epi, class Sched, bool ALIGN_EPI = false, bool SP2 = false>
; __device__ __forceinline__ void gemm_phase(PG8_LAS unsigned char* lds, const Gemm g, const Sched& S, const Epi& E) {
;     ...
;             PG8_WAIT_V(8); PG8_WAIT_L(0); PG8_BAR; PG8_MMA(0, 0, At, B0); PG8_MMA(0, 1, At, B1); PG8_BAR; PG8_SCHED;
;             PG8_LDA(At, 0, 1); PG8_STAGE(PG8_SB(0, 0), b2, voffB); PG8_STAGE(PG8_SB(0, 1), b2 + hstepB, voffB); PG8_STAGE(PG8_SA(0, 0), a2, voffA);
;             PG8_WAIT_V(8); PG8_WAIT_L(0); PG8_BAR; PG8_MMA(1, 0, At, B0); PG8_MMA(1, 1, At, B1); PG8_BAR; PG8_SCHED;
;             PG8_LDB(B0, 1, 0); PG8_LDB(B1, 1, 1); PG8_SCHED; PG8_LDA(At, 1, 0); PG8_STAGE(PG8_SA(0, 1), a2 + hstepA, voffA);
;             PG8_WAIT_V(8); PG8_WAIT_L(0); PG8_BAR; PG8_MMA(0, 0, At, B0); PG8_MMA(0, 1, At, B1); PG8_BAR; PG8_SCHED;
	s_setprio 1
	s_waitcnt lgkmcnt(0)
	v_mfma_f32_16x16x32_bf16 v[60:63], v[128:131], v[180:183], 0
	v_mfma_f32_16x16x32_bf16 v[60:63], v[132:135], v[184:187], v[60:63]
	v_mfma_f32_16x16x32_bf16 v[56:59], v[140:143], v[184:187], 0
	v_mfma_f32_16x16x32_bf16 v[56:59], v[136:139], v[180:183], v[56:59]
	v_mfma_f32_16x16x32_bf16 v[40:43], v[136:139], v[196:199], 0
	v_mfma_f32_16x16x32_bf16 v[40:43], v[140:143], v[200:203], v[40:43]
	v_mfma_f32_16x16x32_bf16 v[44:47], v[132:135], v[200:203], 0
	v_mfma_f32_16x16x32_bf16 v[44:47], v[128:131], v[196:199], v[44:47]
	v_mfma_f32_16x16x32_bf16 v[28:31], v[128:131], v[204:207], 0
	v_mfma_f32_16x16x32_bf16 v[28:31], v[132:135], v[208:211], v[28:31]
	v_mfma_f32_16x16x32_bf16 v[24:27], v[140:143], v[208:211], 0
	v_mfma_f32_16x16x32_bf16 v[24:27], v[136:139], v[204:207], v[24:27]
	v_mfma_f32_16x16x32_bf16 v[8:11], v[136:139], v[212:215], 0
	v_mfma_f32_16x16x32_bf16 v[8:11], v[140:143], v[216:219], v[8:11]
	v_mfma_f32_16x16x32_bf16 v[12:15], v[132:135], v[216:219], 0
	v_mfma_f32_16x16x32_bf16 v[12:15], v[128:131], v[212:215], v[12:15]
	v_mfma_f32_16x16x32_bf16 v[52:55], v[160:163], v[180:183], 0
	v_mfma_f32_16x16x32_bf16 v[52:55], v[168:171], v[184:187], v[52:55]
	v_mfma_f32_16x16x32_bf16 v[48:51], v[176:179], v[184:187], 0
	v_mfma_f32_16x16x32_bf16 v[48:51], v[172:175], v[180:183], v[48:51]
	v_mfma_f32_16x16x32_bf16 v[32:35], v[172:175], v[196:199], 0
	v_mfma_f32_16x16x32_bf16 v[32:35], v[176:179], v[200:203], v[32:35]
	v_mfma_f32_16x16x32_bf16 v[36:39], v[168:171], v[200:203], 0
	v_mfma_f32_16x16x32_bf16 v[36:39], v[160:163], v[196:199], v[36:39]
	v_mfma_f32_16x16x32_bf16 v[20:23], v[160:163], v[204:207], 0
	v_mfma_f32_16x16x32_bf16 v[20:23], v[168:171], v[208:211], v[20:23]
	v_mfma_f32_16x16x32_bf16 v[16:19], v[176:179], v[208:211], 0
	v_mfma_f32_16x16x32_bf16 v[16:19], v[172:175], v[204:207], v[16:19]
	v_mfma_f32_16x16x32_bf16 v[0:3], v[172:175], v[212:215], 0
	v_mfma_f32_16x16x32_bf16 v[0:3], v[176:179], v[216:219], v[0:3]
	s_setprio 2
	s_barrier
	v_mfma_f32_16x16x32_bf16 v[4:7], v[168:171], v[216:219], 0
	v_mfma_f32_16x16x32_bf16 v[4:7], v[160:163], v[212:215], v[4:7]
	s_setprio 0
	s_add_i32 s66, 0, 0x18000
	s_add_i32 s67, 0, 0x1c000
	v_add_u32_e32 v140, s66, v190
	v_add_u32_e32 v176, s67, v190
	ds_read_b128 v[128:131], v140
	ds_read_b128 v[132:135], v140 offset:1024
	ds_read_b128 v[136:139], v140 offset:2048
	ds_read_b128 v[140:143], v140 offset:3072
	ds_read_b128 v[160:163], v176
	ds_read_b128 v[168:171], v176 offset:1024
	ds_read_b128 v[172:175], v176 offset:2048
	ds_read_b128 v[176:179], v176 offset:3072
	s_add_u32 s38, s38, 0x490000
	s_addc_u32 s39, s39, 0
	s_mov_b32 m0, s45
	ds_read_b128 v[180:183], v194 offset:32768
	ds_read_b128 v[184:187], v194 offset:33792
	ds_read_b128 v[196:199], v194 offset:34816
	ds_read_b128 v[200:203], v194 offset:35840
	ds_read_b128 v[204:207], v194 offset:36864
	ds_read_b128 v[208:211], v194 offset:37888
	ds_read_b128 v[212:215], v194 offset:38912
	ds_read_b128 v[216:219], v194 offset:39936
	global_load_lds_dwordx4 v144, s[38:39]
	s_mov_b32 m0, s46
	s_nop 0
	global_load_lds_dwordx4 v148, s[38:39]
	s_waitcnt vmcnt(8)
	s_waitcnt lgkmcnt(0)
	s_barrier
	s_setprio 1
	s_waitcnt lgkmcnt(0)
	v_mfma_f32_16x16x32_bf16 v[124:127], v[128:131], v[180:183], v[124:127]
	v_mfma_f32_16x16x32_bf16 v[124:127], v[132:135], v[184:187], v[124:127]
	v_mfma_f32_16x16x32_bf16 v[120:123], v[140:143], v[184:187], v[120:123]
	v_mfma_f32_16x16x32_bf16 v[120:123], v[136:139], v[180:183], v[120:123]
	v_mfma_f32_16x16x32_bf16 v[104:107], v[136:139], v[196:199], v[104:107]
	v_mfma_f32_16x16x32_bf16 v[104:107], v[140:143], v[200:203], v[104:107]
	v_mfma_f32_16x16x32_bf16 v[108:111], v[132:135], v[200:203], v[108:111]
	v_mfma_f32_16x16x32_bf16 v[108:111], v[128:131], v[196:199], v[108:111]
	v_mfma_f32_16x16x32_bf16 v[92:95], v[128:131], v[204:207], v[92:95]
	v_mfma_f32_16x16x32_bf16 v[92:95], v[132:135], v[208:211], v[92:95]
	v_mfma_f32_16x16x32_bf16 v[88:91], v[140:143], v[208:211], v[88:91]
	v_mfma_f32_16x16x32_bf16 v[88:91], v[136:139], v[204:207], v[88:91]
	v_mfma_f32_16x16x32_bf16 v[72:75], v[136:139], v[212:215], v[72:75]
	v_mfma_f32_16x16x32_bf16 v[72:75], v[140:143], v[216:219], v[72:75]
	v_mfma_f32_16x16x32_bf16 v[76:79], v[132:135], v[216:219], v[76:79]
	v_mfma_f32_16x16x32_bf16 v[76:79], v[128:131], v[212:215], v[76:79]
	v_mfma_f32_16x16x32_bf16 v[116:119], v[160:163], v[180:183], v[116:119]
	v_mfma_f32_16x16x32_bf16 v[116:119], v[168:171], v[184:187], v[116:119]
	v_mfma_f32_16x16x32_bf16 v[112:115], v[176:179], v[184:187], v[112:115]
	v_mfma_f32_16x16x32_bf16 v[112:115], v[172:175], v[180:183], v[112:115]
	v_mfma_f32_16x16x32_bf16 v[96:99], v[172:175], v[196:199], v[96:99]
	v_mfma_f32_16x16x32_bf16 v[96:99], v[176:179], v[200:203], v[96:99]
	v_mfma_f32_16x16x32_bf16 v[100:103], v[168:171], v[200:203], v[100:103]
	v_mfma_f32_16x16x32_bf16 v[100:103], v[160:163], v[196:199], v[100:103]
	v_mfma_f32_16x16x32_bf16 v[84:87], v[160:163], v[204:207], v[84:87]
	v_mfma_f32_16x16x32_bf16 v[84:87], v[168:171], v[208:211], v[84:87]
	v_mfma_f32_16x16x32_bf16 v[80:83], v[176:179], v[208:211], v[80:83]
	v_mfma_f32_16x16x32_bf16 v[80:83], v[172:175], v[204:207], v[80:83]
	v_mfma_f32_16x16x32_bf16 v[64:67], v[172:175], v[212:215], v[64:67]
	v_mfma_f32_16x16x32_bf16 v[64:67], v[176:179], v[216:219], v[64:67]
	s_setprio 2
	s_barrier
; #define PG8_STAGE(bufoff, gbase, voff) do { _Pragma("unroll") for (int _i = 0; _i < 2; ++_i) \
;         __builtin_amdgcn_global_load_lds((const unsigned*)((const char*)(gbase) + (voff)[_i]), (PG8_LAS unsigned*)(lds + (bufoff) + ldsw + _i * 8192), 16, 0, 0); } while (0)
; #define PG8_LDA(dst, b, h) do { _Pragma("unroll") for (int m = 0; m < 4; ++m) _Pragma("unroll") for (int k = 0; k < 2; ++k) dst[m][k] = *(const PG8_LAS bf16x8*)(lds + PG8_SA(b, h) + aoff + m * 2048 + k * 1024); } while (0)
; #define PG8_MMA(ai, bj, At, Bt) do { __builtin_amdgcn_s_setprio(1); _Pragma("unroll") for (int m = 0; m < 4; ++m) _Pragma("unroll") for (int n = 0; n < 2; ++n) _Pragma("unroll") for (int k = 0; k < 2; ++k) \
;         acc[ai][bj][m][n] = __builtin_amdgcn_mfma_f32_16x16x32_bf16(Bt[n][k], At[m][k], acc[ai][bj][m][n], 0, 0, 0); __builtin_amdgcn_s_setprio(0); } while (0)
; #define PG8_WAIT_V(n) asm volatile("s_waitcnt vmcnt(" #n ")" ::: "memory")
; #define PG8_WAIT_L(n) asm volatile("s_waitcnt lgkmcnt(" #n ")" ::: "memory")
; #define PG8_BAR __builtin_amdgcn_s_barrier()
; #define PG8_SCHED __builtin_amdgcn_sched_barrier(0)
; template <class Epi, class Sched, bool ALIGN_EPI = false, bool SP2 = false>
; __device__ __forceinline__ void gemm_phase(PG8_LAS unsigned char* lds, const Gemm g, const Sched& S, const Epi& E) {
;     ...
;             PG8_WAIT_V(8); PG8_WAIT_L(0); PG8_BAR; PG8_MMA(0, 0, At, B0); PG8_MMA(0, 1, At, B1); PG8_BAR; PG8_SCHED;
;             PG8_LDA(At, 1, 1); PG8_STAGE(PG8_SB(1, 0), b3, voffB); PG8_STAGE(PG8_SB(1, 1), b3 + hstepB, voffB); PG8_STAGE(PG8_SA(1, 0), a3, voffA);
;             PG8_WAIT_V(8); PG8_WAIT_L(0); PG8_BAR; PG8_MMA(1, 0, At, B0); PG8_MMA(1, 1, At, B1); PG8_BAR; PG8_SCHED;
	v_mfma_f32_16x16x32_bf16 v[68:71], v[168:171], v[216:219], v[68:71]
	v_mfma_f32_16x16x32_bf16 v[68:71], v[160:163], v[212:215], v[68:71]
	s_setprio 0
	s_add_i32 s38, s66, s40
	s_mov_b32 m0, s38
	ds_read_b128 v[180:183], v194 offset:49152
	ds_read_b128 v[184:187], v194 offset:50176
	ds_read_b128 v[196:199], v194 offset:51200
	ds_read_b128 v[200:203], v194 offset:52224
	ds_read_b128 v[204:207], v194 offset:53248
	ds_read_b128 v[208:211], v194 offset:54272
	ds_read_b128 v[212:215], v194 offset:55296
	ds_read_b128 v[216:219], v194 offset:56320
	global_load_lds_dwordx4 v146, s[98:99]
	s_add_i32 m0, s38, 0x2000
	s_add_u32 s36, s36, 0x200080
	s_addc_u32 s37, s37, 0
	s_add_i32 s38, s67, s40
	global_load_lds_dwordx4 v150, s[98:99]
	s_mov_b32 m0, s38
	s_nop 0
	global_load_lds_dwordx4 v146, s[36:37]
	s_add_i32 m0, s38, 0x2000
	s_nop 0
	global_load_lds_dwordx4 v150, s[36:37]
	s_mov_b32 m0, s47
	s_nop 0
	global_load_lds_dwordx4 v144, s[100:101]
	s_mov_b32 m0, s48
	s_nop 0
	global_load_lds_dwordx4 v148, s[100:101]
	s_waitcnt vmcnt(8)
	s_waitcnt lgkmcnt(0)
	s_barrier
	s_setprio 1
	s_waitcnt lgkmcnt(0)
	v_mfma_f32_16x16x32_bf16 v[60:63], v[128:131], v[180:183], v[60:63]
	v_mfma_f32_16x16x32_bf16 v[60:63], v[132:135], v[184:187], v[60:63]
	v_mfma_f32_16x16x32_bf16 v[56:59], v[140:143], v[184:187], v[56:59]
	v_mfma_f32_16x16x32_bf16 v[56:59], v[136:139], v[180:183], v[56:59]
	v_mfma_f32_16x16x32_bf16 v[40:43], v[136:139], v[196:199], v[40:43]
	v_mfma_f32_16x16x32_bf16 v[40:43], v[140:143], v[200:203], v[40:43]
	v_mfma_f32_16x16x32_bf16 v[44:47], v[132:135], v[200:203], v[44:47]
	v_mfma_f32_16x16x32_bf16 v[44:47], v[128:131], v[196:199], v[44:47]
	v_mfma_f32_16x16x32_bf16 v[28:31], v[128:131], v[204:207], v[28:31]
	v_mfma_f32_16x16x32_bf16 v[28:31], v[132:135], v[208:211], v[28:31]
	v_mfma_f32_16x16x32_bf16 v[24:27], v[140:143], v[208:211], v[24:27]
	v_mfma_f32_16x16x32_bf16 v[24:27], v[136:139], v[204:207], v[24:27]
	v_mfma_f32_16x16x32_bf16 v[8:11], v[136:139], v[212:215], v[8:11]
	v_mfma_f32_16x16x32_bf16 v[8:11], v[140:143], v[216:219], v[8:11]
	v_mfma_f32_16x16x32_bf16 v[12:15], v[132:135], v[216:219], v[12:15]
	v_mfma_f32_16x16x32_bf16 v[12:15], v[128:131], v[212:215], v[12:15]
	v_mfma_f32_16x16x32_bf16 v[52:55], v[160:163], v[180:183], v[52:55]
	v_mfma_f32_16x16x32_bf16 v[52:55], v[168:171], v[184:187], v[52:55]
	v_mfma_f32_16x16x32_bf16 v[48:51], v[176:179], v[184:187], v[48:51]
	v_mfma_f32_16x16x32_bf16 v[48:51], v[172:175], v[180:183], v[48:51]
	v_mfma_f32_16x16x32_bf16 v[32:35], v[172:175], v[196:199], v[32:35]
	v_mfma_f32_16x16x32_bf16 v[32:35], v[176:179], v[200:203], v[32:35]
	v_mfma_f32_16x16x32_bf16 v[36:39], v[168:171], v[200:203], v[36:39]
	v_mfma_f32_16x16x32_bf16 v[36:39], v[160:163], v[196:199], v[36:39]
	v_mfma_f32_16x16x32_bf16 v[20:23], v[160:163], v[204:207], v[20:23]
	v_mfma_f32_16x16x32_bf16 v[20:23], v[168:171], v[208:211], v[20:23]
	v_mfma_f32_16x16x32_bf16 v[16:19], v[176:179], v[208:211], v[16:19]
	v_mfma_f32_16x16x32_bf16 v[16:19], v[172:175], v[204:207], v[16:19]
	v_mfma_f32_16x16x32_bf16 v[0:3], v[172:175], v[212:215], v[0:3]
	v_mfma_f32_16x16x32_bf16 v[0:3], v[176:179], v[216:219], v[0:3]
	s_setprio 2
	s_barrier
	v_mfma_f32_16x16x32_bf16 v[4:7], v[168:171], v[216:219], v[4:7]
	v_mfma_f32_16x16x32_bf16 v[4:7], v[160:163], v[212:215], v[4:7]
	s_setprio 0
	s_add_i32 s65, s65, 2
	s_add_u32 s6, s6, 0x100
	s_addc_u32 s7, s7, 0
	s_add_u32 s63, s63, 0x100
	s_addc_u32 s64, s64, 0
